# barrier-shadow touches extended: fused-LN residual tiles (C->D, E->F) and the depthwise-conv taps/bias of the workgroup's up tiles (D->E)
# baseline (speedup 1.0000x reference)
;     __device__ __forceinline__ void fused(f32x4 (&acc)[2][2][4][2], const GUnit& u, int wr, int wc, int fr, int fq, LAS unsigned char* lds, int wid, int lane) const {
;     ...
;         { u32x4 hw[2][4][2];
; #pragma unroll
;         for (int ai = 0; ai < 2; ++ai)
; #pragma unroll
;             for (int m = 0; m < 4; ++m)
; #pragma unroll
;                 for (int bj = 0; bj < 2; ++bj) hw[ai][m][bj] = *(const u32x4*)(H16 + (size_t)(grow0 + ai * 128 + m * 16) * 1024 + gcol0 + bj * 128);
;     __device__ __forceinline__ bool next_(int i, GUnit& u) const {
;     ...
;         } else if (phase == PH_D) {
;             if (i >= 1 || c >= 256) return false;
;             int pm, pn; pg8::tile_order(64, 4, c, pm, pn); u.pm = pm; u.pn = pn; u.K = 1024;
;             u.A = w + B_MRG + (size_t)pm * 256 * 1024 * 2; u.B = w + W_MIX + (size_t)pn * 256 * 1024 * 2; u.kind = K_MIX; return true;
.Ltch_d_a:
	v_readlane_b32 s5, v254, 6
	v_mbcnt_lo_u32_b32 v245, -1, 0
	v_mbcnt_hi_u32_b32 v245, -1, v245
	s_add_i32 s5, s5, -1
	s_lshl_b32 s5, s5, 6
	s_nop 0
	v_add_u32_e32 v245, s5, v245
	v_readlane_b32 s6, v252, 57
	v_readlane_b32 s7, v252, 58
	s_mov_b32 s8, 11
	s_mov_b32 s9, 0
	v_mov_b32_e32 v248, s9
	v_lshrrev_b32_e32 v246, 1, v245
	v_and_b32_e32 v247, 1, v245
	v_cmp_lt_u32_e32 vcc, 0x7f, v246
	v_lshlrev_b32_e32 v246, s8, v246
	v_lshl_add_u32 v246, v247, 7, v246
	v_cndmask_b32_e32 v247, 0, v248, vcc
	v_add_u32_e32 v246, v246, v247
	s_nop 0
	global_load_dword v244, v246, s[6:7]
	v_cmp_gt_u32_e32 vcc, 64, v245
	s_and_saveexec_b64 s[4:5], vcc
	s_cbranch_execz .Ltch_t2_da
	v_add_u32_e32 v249, 0x1c0, v245
	v_lshrrev_b32_e32 v246, 1, v249
	v_and_b32_e32 v247, 1, v249
	v_lshlrev_b32_e32 v246, s8, v246
	v_lshl_add_u32 v246, v247, 7, v246
	v_add_u32_e32 v246, v246, v248
	s_nop 0
	global_load_dword v244, v246, s[6:7]
.Ltch_t2_da:
	s_or_b64 exec, exec, s[4:5]
	v_readlane_b32 s6, v253, 4
	v_readlane_b32 s7, v253, 5
	v_readlane_b32 s8, v253, 11
	v_readlane_b32 s9, v253, 18
	s_lshl_b32 s8, s8, 19
	s_lshl_b32 s9, s9, 9
	s_add_i32 s8, s8, s9
	s_nop 0
	v_lshrrev_b32_e32 v246, 2, v245
	v_and_b32_e32 v247, 3, v245
	v_lshlrev_b32_e32 v246, 11, v246
	v_lshl_add_u32 v246, v247, 7, v246
	v_add_u32_e32 v246, s8, v246
	s_nop 0
	global_load_dword v244, v246, s[6:7]
	v_add_u32_e32 v249, 0x1c0, v245
	v_lshrrev_b32_e32 v246, 2, v249
	v_and_b32_e32 v247, 3, v249
	v_lshlrev_b32_e32 v246, 11, v246
	v_lshl_add_u32 v246, v247, 7, v246
	v_add_u32_e32 v246, s8, v246
	s_nop 0
	global_load_dword v244, v246, s[6:7]
	v_add_u32_e32 v249, 0x380, v245
	v_cmp_gt_u32_e32 vcc, 0x80, v245
	s_and_saveexec_b64 s[4:5], vcc
	s_cbranch_execz .Ltch_r2_da
	v_lshrrev_b32_e32 v246, 2, v249
	v_and_b32_e32 v247, 3, v249
	v_lshlrev_b32_e32 v246, 11, v246
	v_lshl_add_u32 v246, v247, 7, v246
	v_add_u32_e32 v246, s8, v246
	s_nop 0
	global_load_dword v244, v246, s[6:7]

;     __device__ __forceinline__ bool next_(int i, GUnit& u) const {
;     ...
;         } else if (phase == PH_E) {
;             if (c >= 128 && i < 2) { int pm, pn; pg8::tile_order(64, 4, c, pm, pn); pn = 2 * (pn - 2) + i; u.pm = pm; u.pn = pn;
;                 u.K = 256; u.A = w + WS_P16 + (size_t)pm * 256 * 256 * 2; u.B = w + W_P + (size_t)pn * 256 * 256 * 2; u.kind = K_PP;
;                 return true; }
;             const int L = (c >= 128 ? i - 2 : i) * G + c; if (L >= 1408) return false;
;             int pm, pn; pg8::tile_order(64, 22, L, pm, pn); u.pm = pm; u.pn = pn; u.K = 1024;
;             u.A = w + WS_H16 + (size_t)pm * 256 * 1024 * 2; u.B = w + W_UP + (size_t)pn * 128 * 1024 * 2; u.bhs = (size_t)DFF * 1024 * 2; u.kind = K_FFN; return true;
.Ltch_e_a:
	v_readlane_b32 s5, v254, 6
	v_mbcnt_lo_u32_b32 v245, -1, 0
	v_mbcnt_hi_u32_b32 v245, -1, v245
	s_add_i32 s5, s5, -1
	s_lshl_b32 s5, s5, 6
	s_nop 0
	v_add_u32_e32 v245, s5, v245
	v_readlane_b32 s4, v251, 30
	s_mov_b32 s9, 0
	s_cmp_lg_u32 s4, 0
	s_cbranch_scc1 .Ltch_epp_a
	v_readlane_b32 s6, v251, 39
	v_readlane_b32 s7, v251, 40
	s_mov_b32 s8, 11
	s_mov_b32 s9, 0x540000
	s_branch .Ltch_ego_a

;     __device__ __forceinline__ void operator()(const f32x4 (&acc)[2][2][4][2], const GUnit& u, int wr, int wc, int fr, int fq, LAS unsigned char* lds) const {
;     ...
;             f16x2 w0p[4], w1p[4], w2p[4], bbp[4];
; #pragma unroll
;             for (int n = 0; n < 2; ++n) { const f32x4 a0 = *(const f32x4*)(cw + fb + 4 * n), a1 = *(const f32x4*)(cw + DFF + fb + 4 * n), a2 = *(const f32x4*)(cw + 2 * DFF + fb + 4 * n), ab = *(const f32x4*)(cb + fb + 4 * n);
; #pragma unroll
;                 for (int q = 0; q < 2; ++q) { w0p[2 * n + q] = (f16x2){(f16)a0[2 * q], (f16)a0[2 * q + 1]}; w1p[2 * n + q] = (f16x2){(f16)a1[2 * q], (f16)a1[2 * q + 1]};
;                                               w2p[2 * n + q] = (f16x2){(f16)a2[2 * q], (f16)a2[2 * q + 1]}; bbp[2 * n + q] = (f16x2){(f16)ab[2 * q], (f16)ab[2 * q + 1]}; } }
;     __device__ __forceinline__ bool next_(int i, GUnit& u) const {
;     ...
;         } else if (phase == PH_E) {
;             if (c >= 128 && i < 2) { int pm, pn; pg8::tile_order(64, 4, c, pm, pn); pn = 2 * (pn - 2) + i; u.pm = pm; u.pn = pn;
;                 u.K = 256; u.A = w + WS_P16 + (size_t)pm * 256 * 256 * 2; u.B = w + W_P + (size_t)pn * 256 * 256 * 2; u.kind = K_PP;
;                 return true; }
;             const int L = (c >= 128 ? i - 2 : i) * G + c; if (L >= 1408) return false;
;             int pm, pn; pg8::tile_order(64, 22, L, pm, pn); u.pm = pm; u.pn = pn; u.K = 1024;
;             u.A = w + WS_H16 + (size_t)pm * 256 * 1024 * 2; u.B = w + W_UP + (size_t)pn * 128 * 1024 * 2; u.bhs = (size_t)DFF * 1024 * 2; u.kind = K_FFN; return true;
.Ltch_ego_a:
	v_mov_b32_e32 v248, s9
	v_lshrrev_b32_e32 v246, 1, v245
	v_and_b32_e32 v247, 1, v245
	v_cmp_lt_u32_e32 vcc, 0x7f, v246
	v_lshlrev_b32_e32 v246, s8, v246
	v_lshl_add_u32 v246, v247, 7, v246
	v_cndmask_b32_e32 v247, 0, v248, vcc
	v_add_u32_e32 v246, v246, v247
	s_nop 0
	global_load_dword v244, v246, s[6:7]
	v_cmp_gt_u32_e32 vcc, 64, v245
	s_and_saveexec_b64 s[4:5], vcc
	s_cbranch_execz .Ltch_t2_ea
	v_add_u32_e32 v249, 0x1c0, v245
	v_lshrrev_b32_e32 v246, 1, v249
	v_and_b32_e32 v247, 1, v249
	v_lshlrev_b32_e32 v246, s8, v246
	v_lshl_add_u32 v246, v247, 7, v246
	v_add_u32_e32 v246, v246, v248
	s_nop 0
	global_load_dword v244, v246, s[6:7]
.Ltch_t2_ea:
	s_or_b64 exec, exec, s[4:5]
	v_cmp_gt_u32_e32 vcc, 0x60, v245
	s_and_saveexec_b64 s[4:5], vcc
	s_cbranch_execz .Ltch_c2_ea
	v_readlane_b32 s6, v255, 13
	v_readlane_b32 s7, v255, 14
	v_readlane_b32 s8, v251, 32
	v_lshrrev_b32_e32 v246, 4, v245
	v_bfe_u32 v247, v245, 2, 2
	v_and_b32_e32 v248, 3, v245
	v_lshl_add_u32 v246, v246, 2, s8
	v_cmp_gt_u32_e32 vcc, 22, v246
	v_lshlrev_b32_e32 v246, 9, v246
	v_lshl_add_u32 v246, v248, 7, v246
	s_and_b64 exec, exec, vcc
	s_cbranch_execz .Ltch_c2_ea
	v_cmp_ne_u32_e32 vcc, 3, v247
	v_mul_u32_u24_e32 v248, 0x2c00, v247
	s_mov_b64 s[8:9], exec
	s_and_b64 exec, exec, vcc
	v_add_u32_e32 v248, v246, v248
	s_nop 0
	global_load_dword v244, v248, s[6:7]
	s_andn2_b64 exec, s[8:9], vcc
	v_readlane_b32 s6, v255, 22
	v_readlane_b32 s7, v255, 23
	s_nop 4
	global_load_dword v244, v246, s[6:7]

;     __device__ __forceinline__ bool next_(int i, GUnit& u) const {
;     ...
;         } else {
;             if (i >= 2 || c >= 256) return false;
;             int pm, pn; pg8::tile_order(64, 4, c, pm, pn); u.pm = pm; u.pn = pn;
;             if (i == 0) { u.K = 1024; u.A = w + WS_H16 + (size_t)pm * 256 * 1024 * 2; u.B = w + (par ? W_G2 : W_G) + (size_t)pn * 256 * 1024 * 2; u.kind = K_PG; return true; }
;             u.K = DFF; u.A = w + B_VAL + (size_t)pm * 256 * DFF * 2; u.B = w + (par ? W_D2 : W_D) + (size_t)pn * 256 * DFF * 2; u.kind = K_DOWN; return true;
.Ltch_f_a:
	v_readlane_b32 s5, v254, 6
	v_mbcnt_lo_u32_b32 v245, -1, 0
	v_mbcnt_hi_u32_b32 v245, -1, v245
	s_add_i32 s5, s5, -1
	s_lshl_b32 s5, s5, 6
	s_nop 0
	v_add_u32_e32 v245, s5, v245
	v_readlane_b32 s6, v253, 8
	v_readlane_b32 s7, v253, 9
	s_and_b32 s4, s72, 1
	s_mov_b32 s5, 0x2100000
	s_cmp_eq_u32 s4, 0
	s_cselect_b32 s4, s5, 0x13200000
	s_add_u32 s6, s6, s4
	s_addc_u32 s7, s7, 0
	s_mov_b32 s8, 11
	s_mov_b32 s9, 0
	v_mov_b32_e32 v248, s9
	v_lshrrev_b32_e32 v246, 1, v245
	v_and_b32_e32 v247, 1, v245
	v_cmp_lt_u32_e32 vcc, 0x7f, v246
	v_lshlrev_b32_e32 v246, s8, v246
	v_lshl_add_u32 v246, v247, 7, v246
	v_cndmask_b32_e32 v247, 0, v248, vcc
	v_add_u32_e32 v246, v246, v247
	s_nop 0
	global_load_dword v244, v246, s[6:7]
	v_cmp_gt_u32_e32 vcc, 64, v245
	s_and_saveexec_b64 s[4:5], vcc
	s_cbranch_execz .Ltch_t2_fa
	v_add_u32_e32 v249, 0x1c0, v245
	v_lshrrev_b32_e32 v246, 1, v249
	v_and_b32_e32 v247, 1, v249
	v_lshlrev_b32_e32 v246, s8, v246
	v_lshl_add_u32 v246, v247, 7, v246
	v_add_u32_e32 v246, v246, v248
	s_nop 0
	global_load_dword v244, v246, s[6:7]
